# strategy 6.4: MFMA-first tile head in the MLA loop (first two QK MFMAs of a tile issued right behind the barrier, tile-top temporaries renamed out of the accumulator range)
# baseline (speedup 1.0000x reference)
.LBB0_923:
	s_add_i32 s30, s61, 2
	s_cmpk_gt_u32 s61, 0xfd
	s_cselect_b64 s[44:45], -1, 0
	v_mfma_f32_32x32x16_bf16 v[80:95], v[80:83], v[122:125], 0
	s_and_b64 vcc, exec, s[44:45]
	s_cbranch_vccnz .LBB0_925
	s_and_b32 s6, s30, 2
	s_mulk_i32 s6, 0x5800
	v_add_u32_e32 v207, s6, v238
	v_add_u32_e32 v208, s6, v239
	v_add_u32_e32 v209, s6, v240
	s_waitcnt vmcnt(1)
	ds_write_b128 v207, v[142:145]
	ds_write_b64 v208, v[188:189] offset:128
	s_waitcnt vmcnt(0)
	ds_write_b128 v209, v[146:149] offset:13312
.LBB0_925:
	v_mfma_f32_32x32x16_bf16 v[80:95], v[174:177], v[126:129], v[80:95]
	s_cmpk_gt_u32 s61, 0xfb
	s_cbranch_scc1 .LBB0_927
	global_load_dwordx2 v[188:189], v[202:203], off offset:-4096
	global_load_dwordx4 v[142:145], v96, s[98:99]
	global_load_dwordx4 v[146:149], v200, s[100:101]
	s_add_u32 s98, s98, 0x20000
	s_addc_u32 s99, s99, 0
	s_add_u32 s100, s100, 0x20000
	s_addc_u32 s101, s101, 0
.LBB0_927:
	s_add_i32 s6, s61, -1
	s_and_b32 s77, s61, 2
	s_and_b32 s79, s6, 3
	s_cmp_eq_u32 s61, 0
	s_cselect_b64 s[8:9], -1, 0
	s_mulk_i32 s79, 0x5800
	s_and_b64 s[6:7], s[8:9], exec
	s_mul_i32 s78, s77, 0x5800
	s_cselect_b32 s6, 0, s79
	s_add_i32 s76, s78, 0
	v_add_u32_e32 v199, s76, v241
	v_add_u32_e32 v210, s6, v244
	v_exp_f32_e32 v64, v64
	v_exp_f32_e32 v65, v65
	s_nop 0
	v_add_f32_e32 v207, v65, v64
	v_cvt_pk_bf16_f32 v178, v64, v65
	v_exp_f32_e32 v64, v66
	v_exp_f32_e32 v65, v67
	v_add_f32_e32 v66, v64, v207
	ds_read_b128 v[182:185], v199 offset:96
	ds_read_b128 v[246:249], v199 offset:128
	ds_read_b128 v[250:253], v199 offset:160
	v_add_f32_e32 v66, v65, v66
	v_cvt_pk_bf16_f32 v179, v64, v65
	v_exp_f32_e32 v64, v68
	v_exp_f32_e32 v65, v69
	v_add_f32_e32 v66, v64, v66
	v_add_f32_e32 v66, v65, v66
	v_cvt_pk_bf16_f32 v180, v64, v65
	v_mfma_f32_32x32x16_bf16 v[80:95], v[170:173], v[130:133], v[80:95]
	v_exp_f32_e32 v64, v70
	v_exp_f32_e32 v65, v71
	v_add_f32_e32 v66, v64, v66
	v_add_f32_e32 v170, v65, v66
	v_cvt_pk_bf16_f32 v181, v64, v65
	s_waitcnt lgkmcnt(0)
	v_mfma_f32_32x32x16_bf16 v[80:95], v[182:185], v[134:137], v[80:95]
	ds_read_b128 v[64:67], v210 offset:13376
	ds_read_b128 v[68:71], v210 offset:13408
	ds_read_b128 v[174:177], v210 offset:17984
	ds_read_b128 v[218:221], v210 offset:18016
	v_exp_f32_e32 v72, v72
	v_exp_f32_e32 v73, v73
	v_add_f32_e32 v170, v72, v170
	v_add_f32_e32 v171, v73, v170
	v_cvt_pk_bf16_f32 v170, v72, v73
	v_mfma_f32_32x32x16_bf16 v[80:95], v[246:249], v[154:157], v[80:95]
	v_exp_f32_e32 v72, v74
	v_exp_f32_e32 v73, v75
	v_add_f32_e32 v74, v72, v171
	v_add_f32_e32 v74, v73, v74
	v_cvt_pk_bf16_f32 v171, v72, v73
	v_mfma_f32_32x32x16_bf16 v[80:95], v[250:253], v[158:161], v[80:95]
	v_exp_f32_e32 v72, v76
	v_exp_f32_e32 v73, v77
	v_add_f32_e32 v74, v72, v74
	v_add_f32_e32 v74, v73, v74
	v_cvt_pk_bf16_f32 v172, v72, v73
	s_waitcnt lgkmcnt(0)
	v_mfma_f32_32x32x16_bf16 v[16:31], v[64:67], v[162:165], v[16:31]
	v_exp_f32_e32 v64, v78
	v_exp_f32_e32 v65, v79
	v_add_f32_e32 v66, v64, v74
	v_add_f32_e32 v246, v65, v66
	v_cvt_pk_bf16_f32 v173, v64, v65
	v_mfma_f32_32x32x16_bf16 v[0:15], v[174:177], v[162:165], v[0:15]
	ds_read_b128 v[64:67], v199 offset:6656
	ds_read_b128 v[182:185], v199 offset:6688
	ds_read_b128 v[174:177], v199 offset:6720
	v_cmp_nge_f32_e64 s[6:7], s48, v246
	v_cmp_gt_f32_e32 vcc, s49, v246
	v_mfma_f32_32x32x16_bf16 v[16:31], v[68:71], v[166:169], v[16:31]
	v_exp_f32_e32 v68, v80
	v_exp_f32_e32 v69, v81
	s_nop 0
	v_add_f32_e32 v70, v69, v68
	v_cvt_pk_bf16_f32 v162, v68, v69
	v_exp_f32_e32 v80, v82
	v_exp_f32_e32 v81, v83
	v_add_f32_e32 v82, v80, v70
	v_mfma_f32_32x32x16_bf16 v[0:15], v[218:221], v[166:169], v[0:15]
	s_and_b64 vcc, s[8:9], vcc
	s_or_b64 s[6:7], s[6:7], vcc
	v_add_u32_e32 v211, s76, v243
	ds_read_b128 v[166:169], v199 offset:6752
	ds_read_b128 v[218:221], v199 offset:6784
	ds_read_b128 v[248:251], v199 offset:6816
	s_waitcnt lgkmcnt(3)
	v_mfma_f32_32x32x16_bf16 v[64:79], v[64:67], v[98:101], 0
	v_add_f32_e32 v82, v81, v82
	v_cvt_pk_bf16_f32 v163, v80, v81
	v_mfma_f32_32x32x16_bf16 v[64:79], v[182:185], v[102:105], v[64:79]
	v_exp_f32_e32 v80, v84
	v_exp_f32_e32 v81, v85
	v_add_f32_e32 v82, v80, v82
	v_add_f32_e32 v82, v81, v82
	v_cvt_pk_bf16_f32 v164, v80, v81
	v_mfma_f32_32x32x16_bf16 v[64:79], v[174:177], v[106:109], v[64:79]
	v_exp_f32_e32 v80, v86
	v_exp_f32_e32 v81, v87
	v_add_f32_e32 v82, v80, v82
	v_add_f32_e32 v174, v81, v82
	v_cvt_pk_bf16_f32 v165, v80, v81
	s_waitcnt lgkmcnt(0)
	v_mfma_f32_32x32x16_bf16 v[64:79], v[166:169], v[110:113], v[64:79]
	ds_read_b128 v[80:83], v211 offset:13312
	ds_read_b128 v[84:87], v211 offset:13344
	ds_read_b128 v[182:185], v211 offset:17920
	ds_read_b128 v[222:225], v211 offset:17952
	v_exp_f32_e32 v88, v88
	v_exp_f32_e32 v89, v89
	v_add_f32_e32 v166, v88, v174
	v_add_f32_e32 v166, v89, v166
	v_cvt_pk_bf16_f32 v174, v88, v89
	v_mfma_f32_32x32x16_bf16 v[64:79], v[218:221], v[114:117], v[64:79]
	v_exp_f32_e32 v88, v90
	v_exp_f32_e32 v89, v91
	v_add_f32_e32 v90, v88, v166
	v_add_f32_e32 v90, v89, v90
	v_cvt_pk_bf16_f32 v175, v88, v89
	v_mfma_f32_32x32x16_bf16 v[64:79], v[248:251], v[118:121], v[64:79]
	v_exp_f32_e32 v88, v92
	v_exp_f32_e32 v89, v93
	v_add_f32_e32 v90, v88, v90
	v_add_f32_e32 v90, v89, v90
	v_cvt_pk_bf16_f32 v176, v88, v89
	s_waitcnt lgkmcnt(0)
; #define LAS __attribute__((address_space(3)))
; template <int MODE, bool FAST> __device__ __forceinline__ bool attn_unit(LAS unsigned char* lds, const AttU& U, const int wv) {
;     ...
;     pb[1][0] = (bf16x8){0, 0, 0, 0, 0, 0, 0, 0}; pb[1][1] = pb[1][0];
;     ATT_QK(0, 0, 0);
;     bf16x8 kpre[NPRE > 0 ? NPRE : 1];
; #pragma unroll
;     for (int i_ = 0; i_ < NPRE; ++i_) kpre[i_] = *(LAS const bf16x8*)(lds + koff + i_ * 32);
	v_mfma_f32_32x32x16_bf16 v[48:63], v[80:83], v[178:181], v[48:63]
	v_exp_f32_e32 v80, v94
	v_exp_f32_e32 v81, v95
	v_add_f32_e32 v82, v80, v90
	v_add_f32_e32 v247, v81, v82
	v_cvt_pk_bf16_f32 v177, v80, v81
	v_mfma_f32_32x32x16_bf16 v[32:47], v[182:185], v[178:181], v[32:47]
	ds_read_b128 v[80:83], v199 offset:6656
	ds_read_b128 v[182:185], v199 offset:6688
	ds_read_b128 v[178:181], v199 offset:6720
	v_cmp_nge_f32_e64 s[10:11], s48, v247
	v_cmp_gt_f32_e32 vcc, s49, v247
	v_mfma_f32_32x32x16_bf16 v[48:63], v[84:87], v[170:173], v[48:63]
	v_exp_f32_e32 v64, v64
	v_exp_f32_e32 v65, v65
	s_nop 0
	v_add_f32_e32 v84, v65, v64
	v_cvt_pk_bf16_f32 v166, v64, v65
	v_exp_f32_e32 v64, v66
	v_exp_f32_e32 v65, v67
	v_add_f32_e32 v66, v64, v84
	v_mfma_f32_32x32x16_bf16 v[32:47], v[222:225], v[170:173], v[32:47]
	s_and_b64 s[8:9], s[8:9], vcc
	s_or_b64 s[8:9], s[8:9], s[10:11]
	ds_read_b128 v[170:173], v199 offset:6752
	ds_read_b128 v[218:221], v199 offset:6784
	ds_read_b128 v[222:225], v199 offset:6816
	s_waitcnt lgkmcnt(3)
	v_mfma_f32_32x32x16_bf16 v[80:95], v[80:83], v[122:125], 0
	v_add_f32_e32 v66, v65, v66
	v_cvt_pk_bf16_f32 v167, v64, v65
	v_mfma_f32_32x32x16_bf16 v[80:95], v[182:185], v[126:129], v[80:95]
	v_exp_f32_e32 v64, v68
	v_exp_f32_e32 v65, v69
	v_add_f32_e32 v66, v64, v66
	v_add_f32_e32 v66, v65, v66
	v_cvt_pk_bf16_f32 v168, v64, v65
	v_mfma_f32_32x32x16_bf16 v[80:95], v[178:181], v[130:133], v[80:95]
	v_exp_f32_e32 v64, v70
	v_exp_f32_e32 v65, v71
	v_add_f32_e32 v66, v64, v66
	v_add_f32_e32 v178, v65, v66
	v_cvt_pk_bf16_f32 v169, v64, v65
	s_waitcnt lgkmcnt(0)
	v_mfma_f32_32x32x16_bf16 v[80:95], v[170:173], v[134:137], v[80:95]
	ds_read_b128 v[64:67], v211 offset:13312
	ds_read_b128 v[68:71], v211 offset:13344
	ds_read_b128 v[182:185], v211 offset:17920
	ds_read_b128 v[248:251], v211 offset:17952
	v_exp_f32_e32 v72, v72
	v_exp_f32_e32 v73, v73
	v_add_f32_e32 v170, v72, v178
	v_add_f32_e32 v170, v73, v170
	v_cvt_pk_bf16_f32 v178, v72, v73
	v_mfma_f32_32x32x16_bf16 v[80:95], v[218:221], v[154:157], v[80:95]
	v_exp_f32_e32 v72, v74
	v_exp_f32_e32 v73, v75
	v_add_f32_e32 v74, v72, v170
	v_add_f32_e32 v74, v73, v74
	v_cvt_pk_bf16_f32 v179, v72, v73
	v_mfma_f32_32x32x16_bf16 v[80:95], v[222:225], v[158:161], v[80:95]
	v_exp_f32_e32 v72, v76
	v_exp_f32_e32 v73, v77
	v_add_f32_e32 v74, v72, v74
	v_add_f32_e32 v74, v73, v74
	v_cvt_pk_bf16_f32 v180, v72, v73
	s_waitcnt lgkmcnt(0)
	v_mfma_f32_32x32x16_bf16 v[16:31], v[64:67], v[162:165], v[16:31]
	v_exp_f32_e32 v64, v78
	v_exp_f32_e32 v65, v79
	v_add_f32_e32 v66, v64, v74
	v_add_f32_e32 v210, v65, v66
	v_cvt_pk_bf16_f32 v181, v64, v65
	v_mfma_f32_32x32x16_bf16 v[0:15], v[182:185], v[162:165], v[0:15]
	v_add_u32_e32 v226, s78, v242
	ds_read_b128 v[64:67], v226 offset:22528
	ds_read_b128 v[170:173], v226 offset:22560
	ds_read_b128 v[182:185], v226 offset:22592
	v_cmp_nge_f32_e64 s[10:11], s48, v210
	v_mfma_f32_32x32x16_bf16 v[16:31], v[68:71], v[174:177], v[16:31]
	v_exp_f32_e32 v68, v80
	v_exp_f32_e32 v69, v81
	s_nop 0
	v_add_f32_e32 v70, v69, v68
	v_cvt_pk_bf16_f32 v162, v68, v69
	v_exp_f32_e32 v80, v82
	v_exp_f32_e32 v81, v83
	v_add_f32_e32 v82, v80, v70
	v_mfma_f32_32x32x16_bf16 v[0:15], v[248:251], v[174:177], v[0:15]
	ds_read_b128 v[174:177], v226 offset:22624
	ds_read_b128 v[218:221], v226 offset:22656
	ds_read_b128 v[222:225], v226 offset:22688
	s_waitcnt lgkmcnt(3)
	v_mfma_f32_32x32x16_bf16 v[64:79], v[64:67], v[98:101], 0
	v_add_f32_e32 v82, v81, v82
	v_cvt_pk_bf16_f32 v163, v80, v81
	v_mfma_f32_32x32x16_bf16 v[64:79], v[170:173], v[102:105], v[64:79]
	v_exp_f32_e32 v80, v84
	v_exp_f32_e32 v81, v85
	v_add_f32_e32 v82, v80, v82
	v_add_f32_e32 v82, v81, v82
	v_cvt_pk_bf16_f32 v164, v80, v81
	v_mfma_f32_32x32x16_bf16 v[64:79], v[182:185], v[106:109], v[64:79]
	v_exp_f32_e32 v80, v86
	v_exp_f32_e32 v81, v87
	v_add_f32_e32 v82, v80, v82
	v_add_f32_e32 v170, v81, v82
	v_cvt_pk_bf16_f32 v165, v80, v81
	s_waitcnt lgkmcnt(0)
	v_mfma_f32_32x32x16_bf16 v[64:79], v[174:177], v[110:113], v[64:79]
	ds_read_b128 v[80:83], v211 offset:13376
	ds_read_b128 v[84:87], v211 offset:13408
	ds_read_b128 v[182:185], v211 offset:17984
	ds_read_b128 v[248:251], v211 offset:18016
	v_exp_f32_e32 v88, v88
	v_exp_f32_e32 v89, v89
	v_add_f32_e32 v170, v88, v170
	v_add_f32_e32 v171, v89, v170
	v_cvt_pk_bf16_f32 v170, v88, v89
	v_mfma_f32_32x32x16_bf16 v[64:79], v[218:221], v[114:117], v[64:79]
	v_exp_f32_e32 v88, v90
	v_exp_f32_e32 v89, v91
	v_add_f32_e32 v90, v88, v171
	v_add_f32_e32 v90, v89, v90
	v_cvt_pk_bf16_f32 v171, v88, v89
	v_mfma_f32_32x32x16_bf16 v[64:79], v[222:225], v[118:121], v[64:79]
	v_exp_f32_e32 v88, v92
	v_exp_f32_e32 v89, v93
	v_add_f32_e32 v90, v88, v90
	v_add_f32_e32 v90, v89, v90
	v_cvt_pk_bf16_f32 v172, v88, v89
	s_waitcnt lgkmcnt(0)
	v_mfma_f32_32x32x16_bf16 v[48:63], v[80:83], v[166:169], v[48:63]
	v_exp_f32_e32 v80, v94
	v_exp_f32_e32 v81, v95
	v_add_f32_e32 v82, v80, v90
	v_add_f32_e32 v211, v81, v82
	v_cvt_pk_bf16_f32 v173, v80, v81
	v_mfma_f32_32x32x16_bf16 v[32:47], v[182:185], v[166:169], v[32:47]
	ds_read_b128 v[80:83], v226 offset:22528
	ds_read_b128 v[182:185], v226 offset:22560
	ds_read_b128 v[174:177], v226 offset:22592
	v_cmp_nge_f32_e64 s[12:13], s48, v211
	v_mfma_f32_32x32x16_bf16 v[48:63], v[84:87], v[178:181], v[48:63]
	s_barrier
	s_waitcnt lgkmcnt(0)
	v_mfma_f32_32x32x16_bf16 v[32:47], v[248:251], v[178:181], v[32:47]
	v_mfma_f32_32x32x16_bf16 v[80:95], v[80:83], v[122:125], 0
	s_cmpk_gt_u32 s61, 0xfc
	s_cbranch_scc1 .LBB0_933
	v_add_u32_e32 v207, s79, v238
	v_add_u32_e32 v208, s79, v245
	v_add_u32_e32 v209, s79, v198
	s_waitcnt vmcnt(1)
	ds_write_b128 v207, v[150:153]
	s_waitcnt vmcnt(0)
	ds_write_b64 v208, v[190:191] offset:128
	ds_write_b128 v209, v[138:141] offset:13312
.LBB0_933:
	v_mfma_f32_32x32x16_bf16 v[80:95], v[182:185], v[126:129], v[80:95]
	s_cmpk_gt_u32 s61, 0xfa
	s_cbranch_scc1 .LBB0_935
	global_load_dwordx2 v[190:191], v[202:203], off
	global_load_dwordx4 v[150:153], v96, s[98:99]
	global_load_dwordx4 v[138:141], v200, s[100:101]
	s_add_u32 s98, s98, 0x20000
	s_addc_u32 s99, s99, 0
	s_add_u32 s100, s100, 0x20000
	s_addc_u32 s101, s101, 0
.LBB0_935:
	s_or_b64 s[6:7], s[8:9], s[6:7]
	v_add_f32_e32 v207, v204, v246
	v_add_f32_e32 v208, v205, v247
	s_or_b64 s[6:7], s[6:7], s[10:11]
	s_or_b64 s[6:7], s[6:7], s[12:13]
	v_add_f32_e32 v178, v207, v210
	v_add_f32_e32 v179, v208, v211
	s_xor_b32 s10, s77, 2
	v_add_u32_e32 v222, s78, v244
	v_exp_f32_e32 v64, v64
	v_exp_f32_e32 v65, v65
	s_nop 0
	v_add_f32_e32 v207, v65, v64
	v_cvt_pk_bf16_f32 v166, v64, v65
	v_exp_f32_e32 v64, v66
	v_exp_f32_e32 v65, v67
	v_add_f32_e32 v66, v64, v207
	ds_read_b128 v[204:207], v199 offset:22624
	ds_read_b128 v[208:211], v199 offset:22656
	ds_read_b128 v[218:221], v199 offset:22688
	v_add_f32_e32 v66, v65, v66
	v_cvt_pk_bf16_f32 v167, v64, v65
	v_exp_f32_e32 v64, v68
	v_exp_f32_e32 v65, v69
	v_add_f32_e32 v66, v64, v66
	v_add_f32_e32 v66, v65, v66
	v_cvt_pk_bf16_f32 v168, v64, v65
	v_mfma_f32_32x32x16_bf16 v[80:95], v[174:177], v[130:133], v[80:95]
	v_exp_f32_e32 v64, v70
	v_exp_f32_e32 v65, v71
	v_add_f32_e32 v66, v64, v66
	v_add_f32_e32 v174, v65, v66
	v_cvt_pk_bf16_f32 v169, v64, v65
	s_waitcnt lgkmcnt(0)
	v_mfma_f32_32x32x16_bf16 v[80:95], v[204:207], v[134:137], v[80:95]
	ds_read_b128 v[64:67], v222 offset:13376
	ds_read_b128 v[68:71], v222 offset:13408
	ds_read_b128 v[180:183], v222 offset:17984
	ds_read_b128 v[222:225], v222 offset:18016
	v_exp_f32_e32 v72, v72
	v_exp_f32_e32 v73, v73
	v_add_f32_e32 v174, v72, v174
	v_add_f32_e32 v175, v73, v174
	v_cvt_pk_bf16_f32 v174, v72, v73
	v_mfma_f32_32x32x16_bf16 v[80:95], v[208:211], v[154:157], v[80:95]
	v_exp_f32_e32 v72, v74
	v_exp_f32_e32 v73, v75
	v_add_f32_e32 v74, v72, v175
	v_add_f32_e32 v74, v73, v74
	v_cvt_pk_bf16_f32 v175, v72, v73
	v_mfma_f32_32x32x16_bf16 v[80:95], v[218:221], v[158:161], v[80:95]
	v_exp_f32_e32 v72, v76
	v_exp_f32_e32 v73, v77
	v_add_f32_e32 v74, v72, v74
	v_add_f32_e32 v74, v73, v74
	v_cvt_pk_bf16_f32 v176, v72, v73
	s_waitcnt lgkmcnt(0)
	v_mfma_f32_32x32x16_bf16 v[16:31], v[64:67], v[162:165], v[16:31]
	v_exp_f32_e32 v64, v78
	v_exp_f32_e32 v65, v79
	v_add_f32_e32 v66, v64, v74
	v_add_f32_e32 v204, v65, v66
	v_cvt_pk_bf16_f32 v177, v64, v65
	v_mfma_f32_32x32x16_bf16 v[0:15], v[180:183], v[162:165], v[0:15]
	ds_read_b128 v[64:67], v199 offset:29184
	ds_read_b128 v[180:183], v199 offset:29216
	ds_read_b128 v[208:211], v199 offset:29248
	v_cmp_nge_f32_e32 vcc, s48, v204
	v_mfma_f32_32x32x16_bf16 v[16:31], v[68:71], v[170:173], v[16:31]
	v_mfma_f32_32x32x16_bf16 v[0:15], v[222:225], v[170:173], v[0:15]
	v_mad_u32_u24 v68, v187, s69, v186
	v_add_u32_e32 v206, s76, v68
	v_exp_f32_e32 v68, v80
	v_exp_f32_e32 v69, v81
	s_nop 0
	v_add_f32_e32 v70, v69, v68
	v_cvt_pk_bf16_f32 v162, v68, v69
	v_exp_f32_e32 v80, v82
	ds_read_b128 v[170:173], v199 offset:29280
	ds_read_b128 v[218:221], v199 offset:29312
	ds_read_b128 v[222:225], v199 offset:29344
	v_exp_f32_e32 v81, v83
	v_add_f32_e32 v82, v80, v70
	s_waitcnt lgkmcnt(3)
	v_mfma_f32_32x32x16_bf16 v[64:79], v[64:67], v[98:101], 0
	v_add_f32_e32 v82, v81, v82
	v_cvt_pk_bf16_f32 v163, v80, v81
	v_mfma_f32_32x32x16_bf16 v[64:79], v[180:183], v[102:105], v[64:79]
	v_exp_f32_e32 v80, v84
	v_exp_f32_e32 v81, v85
	v_add_f32_e32 v82, v80, v82
	v_add_f32_e32 v82, v81, v82
	v_cvt_pk_bf16_f32 v164, v80, v81
	v_mfma_f32_32x32x16_bf16 v[64:79], v[208:211], v[106:109], v[64:79]
	v_exp_f32_e32 v80, v86
	v_exp_f32_e32 v81, v87
	v_add_f32_e32 v82, v80, v82
	v_add_f32_e32 v184, v81, v82
	v_cvt_pk_bf16_f32 v165, v80, v81
	s_waitcnt lgkmcnt(0)
	v_mfma_f32_32x32x16_bf16 v[64:79], v[170:173], v[110:113], v[64:79]
	ds_read_b128 v[80:83], v206 offset:35840
	ds_read_b128 v[84:87], v206 offset:35872
	ds_read_b128 v[180:183], v206 offset:40448
	ds_read_b128 v[208:211], v206 offset:40480
	v_exp_f32_e32 v88, v88
	v_exp_f32_e32 v89, v89
	v_add_f32_e32 v170, v88, v184
	v_add_f32_e32 v171, v89, v170
	v_cvt_pk_bf16_f32 v170, v88, v89
	v_mfma_f32_32x32x16_bf16 v[64:79], v[218:221], v[114:117], v[64:79]
	v_exp_f32_e32 v88, v90
	v_exp_f32_e32 v89, v91
	v_add_f32_e32 v90, v88, v171
	v_add_f32_e32 v90, v89, v90
	v_cvt_pk_bf16_f32 v171, v88, v89
	v_mfma_f32_32x32x16_bf16 v[64:79], v[222:225], v[118:121], v[64:79]
	v_exp_f32_e32 v88, v92
	v_exp_f32_e32 v89, v93
	v_add_f32_e32 v90, v88, v90
	v_add_f32_e32 v90, v89, v90
	v_cvt_pk_bf16_f32 v172, v88, v89
	s_waitcnt lgkmcnt(0)
	v_mfma_f32_32x32x16_bf16 v[48:63], v[80:83], v[166:169], v[48:63]
	v_exp_f32_e32 v80, v94
	v_exp_f32_e32 v81, v95
	v_add_f32_e32 v82, v80, v90
	v_add_f32_e32 v205, v81, v82
	v_cvt_pk_bf16_f32 v173, v80, v81
	v_mfma_f32_32x32x16_bf16 v[32:47], v[180:183], v[166:169], v[32:47]
	ds_read_b128 v[80:83], v199 offset:29184
	ds_read_b128 v[166:169], v199 offset:29216
	ds_read_b128 v[182:185], v199 offset:29248
	s_or_b64 s[8:9], s[6:7], vcc
	v_cmp_nge_f32_e32 vcc, s48, v205
	v_add_f32_e32 v204, v178, v204
	v_add_f32_e32 v205, v179, v205
	v_mfma_f32_32x32x16_bf16 v[48:63], v[84:87], v[174:177], v[48:63]
	v_exp_f32_e32 v64, v64
	v_exp_f32_e32 v65, v65
	s_nop 0
	v_add_f32_e32 v84, v65, v64
	v_cvt_pk_bf16_f32 v178, v64, v65
	v_exp_f32_e32 v64, v66
	v_exp_f32_e32 v65, v67
	v_add_f32_e32 v66, v64, v84
	v_mfma_f32_32x32x16_bf16 v[32:47], v[208:211], v[174:177], v[32:47]
	ds_read_b128 v[174:177], v199 offset:29280
	ds_read_b128 v[208:211], v199 offset:29312
	ds_read_b128 v[218:221], v199 offset:29344
	s_waitcnt lgkmcnt(3)
; #define LAS __attribute__((address_space(3)))
; template <int MODE, bool FAST> __device__ __forceinline__ bool attn_unit(LAS unsigned char* lds, const AttU& U, const int wv) {
;     ...
;     pb[1][0] = (bf16x8){0, 0, 0, 0, 0, 0, 0, 0}; pb[1][1] = pb[1][0];
;     ATT_QK(0, 0, 0);
;     bf16x8 kpre[NPRE > 0 ? NPRE : 1];
; #pragma unroll
;     for (int i_ = 0; i_ < NPRE; ++i_) kpre[i_] = *(LAS const bf16x8*)(lds + koff + i_ * 32);
;     ...
;     if constexpr (FAST) {
;         for (int t2 = U.kt0; t2 < U.kt1; t2 += 2) { ATT_TILE(t2, 4, rk, rr, rv); ATT_TILE(t2 + 1, 4, rk2, rr2, rv2); }
	v_mfma_f32_32x32x16_bf16 v[80:95], v[80:83], v[122:125], 0
	v_add_f32_e32 v66, v65, v66
	v_cvt_pk_bf16_f32 v179, v64, v65
	v_mfma_f32_32x32x16_bf16 v[80:95], v[166:169], v[126:129], v[80:95]
	v_exp_f32_e32 v64, v68
	v_exp_f32_e32 v65, v69
	v_add_f32_e32 v66, v64, v66
	v_add_f32_e32 v66, v65, v66
	v_cvt_pk_bf16_f32 v180, v64, v65
	v_mfma_f32_32x32x16_bf16 v[80:95], v[182:185], v[130:133], v[80:95]
	v_exp_f32_e32 v64, v70
	v_exp_f32_e32 v65, v71
	v_add_f32_e32 v66, v64, v66
	v_add_f32_e32 v182, v65, v66
	v_cvt_pk_bf16_f32 v181, v64, v65
	s_waitcnt lgkmcnt(0)
	v_mfma_f32_32x32x16_bf16 v[80:95], v[174:177], v[134:137], v[80:95]
	ds_read_b128 v[64:67], v206 offset:35840
	ds_read_b128 v[68:71], v206 offset:35872
	ds_read_b128 v[166:169], v206 offset:40448
	ds_read_b128 v[222:225], v206 offset:40480
	v_exp_f32_e32 v72, v72
	v_exp_f32_e32 v73, v73
	v_add_f32_e32 v174, v72, v182
	v_add_f32_e32 v174, v73, v174
	v_cvt_pk_bf16_f32 v182, v72, v73
	v_mfma_f32_32x32x16_bf16 v[80:95], v[208:211], v[154:157], v[80:95]
	v_exp_f32_e32 v72, v74
	v_exp_f32_e32 v73, v75
	v_add_f32_e32 v74, v72, v174
	v_add_f32_e32 v74, v73, v74
	v_cvt_pk_bf16_f32 v183, v72, v73
	v_mfma_f32_32x32x16_bf16 v[80:95], v[218:221], v[158:161], v[80:95]
	v_exp_f32_e32 v72, v76
	v_exp_f32_e32 v73, v77
	v_add_f32_e32 v74, v72, v74
	v_add_f32_e32 v74, v73, v74
	v_cvt_pk_bf16_f32 v184, v72, v73
	s_waitcnt lgkmcnt(0)
	v_mfma_f32_32x32x16_bf16 v[16:31], v[64:67], v[162:165], v[16:31]
	v_exp_f32_e32 v64, v78
	v_exp_f32_e32 v65, v79
	v_add_f32_e32 v66, v64, v74
	v_add_f32_e32 v226, v65, v66
	v_cvt_pk_bf16_f32 v185, v64, v65
	v_mfma_f32_32x32x16_bf16 v[0:15], v[166:169], v[162:165], v[0:15]
	s_mulk_i32 s10, 0x5800
	v_add_u32_e32 v199, s10, v242
	ds_read_b128 v[64:67], v199
	ds_read_b128 v[164:167], v199 offset:32
	ds_read_b128 v[174:177], v199 offset:64
	v_cmp_nge_f32_e64 s[6:7], s48, v226
	v_mfma_f32_32x32x16_bf16 v[16:31], v[68:71], v[170:173], v[16:31]
	v_exp_f32_e32 v68, v80
	v_exp_f32_e32 v69, v81
	s_nop 0
	v_add_f32_e32 v70, v69, v68
	v_cvt_pk_bf16_f32 v162, v68, v69
	v_exp_f32_e32 v80, v82
	v_exp_f32_e32 v81, v83
	v_add_f32_e32 v82, v80, v70
	v_mfma_f32_32x32x16_bf16 v[0:15], v[222:225], v[170:173], v[0:15]
	s_or_b64 s[8:9], s[8:9], vcc
	ds_read_b128 v[168:171], v199 offset:96
	ds_read_b128 v[208:211], v199 offset:128
	ds_read_b128 v[218:221], v199 offset:160
	s_waitcnt lgkmcnt(3)
	v_mfma_f32_32x32x16_bf16 v[64:79], v[64:67], v[98:101], 0
	v_add_f32_e32 v82, v81, v82
	v_cvt_pk_bf16_f32 v163, v80, v81
	v_mfma_f32_32x32x16_bf16 v[64:79], v[164:167], v[102:105], v[64:79]
	v_exp_f32_e32 v80, v84
	v_exp_f32_e32 v81, v85
	v_add_f32_e32 v82, v80, v82
	v_add_f32_e32 v82, v81, v82
	v_cvt_pk_bf16_f32 v164, v80, v81
	v_mfma_f32_32x32x16_bf16 v[64:79], v[174:177], v[106:109], v[64:79]
	v_exp_f32_e32 v80, v86
	v_exp_f32_e32 v81, v87
	v_add_f32_e32 v82, v80, v82
	v_add_f32_e32 v166, v81, v82
	v_cvt_pk_bf16_f32 v165, v80, v81
	s_waitcnt lgkmcnt(0)
	v_mfma_f32_32x32x16_bf16 v[64:79], v[168:171], v[110:113], v[64:79]
	ds_read_b128 v[80:83], v206 offset:35904
	ds_read_b128 v[84:87], v206 offset:35936
	ds_read_b128 v[222:225], v206 offset:40512
	ds_read_b128 v[246:249], v206 offset:40544
	v_exp_f32_e32 v88, v88
	v_exp_f32_e32 v89, v89
	v_add_f32_e32 v166, v88, v166
	v_add_f32_e32 v167, v89, v166
	v_cvt_pk_bf16_f32 v166, v88, v89
	v_mfma_f32_32x32x16_bf16 v[64:79], v[208:211], v[114:117], v[64:79]
	v_exp_f32_e32 v88, v90
	v_exp_f32_e32 v89, v91
	v_add_f32_e32 v90, v88, v167
	v_add_f32_e32 v90, v89, v90
	v_cvt_pk_bf16_f32 v167, v88, v89
	v_mfma_f32_32x32x16_bf16 v[64:79], v[218:221], v[118:121], v[64:79]
	v_exp_f32_e32 v88, v92
	v_exp_f32_e32 v89, v93
	v_add_f32_e32 v90, v88, v90
	v_add_f32_e32 v90, v89, v90
	v_cvt_pk_bf16_f32 v168, v88, v89
	s_waitcnt lgkmcnt(0)
	v_mfma_f32_32x32x16_bf16 v[48:63], v[80:83], v[178:181], v[48:63]
	v_exp_f32_e32 v80, v94
	v_exp_f32_e32 v81, v95
	v_add_f32_e32 v82, v80, v90
	v_add_f32_e32 v227, v81, v82
	v_cvt_pk_bf16_f32 v169, v80, v81
	v_mfma_f32_32x32x16_bf16 v[32:47], v[222:225], v[178:181], v[32:47]
	ds_read_b128 v[80:83], v199
	ds_read_b128 v[174:177], v199 offset:32
	ds_read_b128 v[170:173], v199 offset:64
	s_or_b64 s[6:7], s[8:9], s[6:7]
	v_cmp_nge_f32_e32 vcc, s48, v227
	s_or_b64 s[6:7], s[6:7], vcc
	s_cmp_lg_u64 s[6:7], 0
	s_cselect_b64 s[6:7], -1, 0
	s_or_b64 s[42:43], s[42:43], s[6:7]
	v_mfma_f32_32x32x16_bf16 v[48:63], v[84:87], v[182:185], v[48:63]
	v_add_f32_e64 v204, v204, v226
	v_add_f32_e64 v205, v205, v227
	s_barrier
	s_waitcnt lgkmcnt(0)
	v_mfma_f32_32x32x16_bf16 v[32:47], v[246:249], v[182:185], v[32:47]
	s_add_u32 s40, s40, 0x40000
	s_mov_b64 s[6:7], 0x2000
	s_addc_u32 s41, s41, 0
	v_lshl_add_u64 v[202:203], v[202:203], 0, s[6:7]
	s_and_b64 vcc, exec, s[44:45]
	s_cbranch_vccnz .LBB0_937
	s_mov_b32 s61, s30
	s_branch .LBB0_923
